# phase 1: workgroups 128..255 run their sample-row unit before their two tiles (staggers the store bursts of the two grid halves)
# speedup vs baseline: 1.0141x; 1.0066x over previous
_Z14fwd_megakernel6Params:
	s_mov_b32 s92, s2
	s_mov_b32 s99, 0
	s_load_dwordx8 s[84:91], s[0:1], 0x80
	s_load_dword s2, s[0:1], 0xa0
	s_load_dwordx16 s[56:71], s[0:1], 0x0
	s_load_dwordx16 s[20:35], s[0:1], 0x40
	v_and_b32_e32 v162, 0x3ff, v0
	v_cmp_eq_u32_e64 s[4:5], 0, v162
	s_waitcnt lgkmcnt(0)
	v_writelane_b32 v251, s2, 0
	s_add_u32 s2, s0, 0x98
	s_addc_u32 s3, s1, 0
	v_writelane_b32 v251, s2, 1
	s_nop 1
	v_writelane_b32 v251, s3, 2
	s_mov_b64 s[2:3], exec
	v_writelane_b32 v251, s4, 3
	s_nop 1
	v_writelane_b32 v251, s5, 4
	s_and_b64 s[4:5], s[2:3], s[4:5]
	s_mov_b64 exec, s[4:5]
	s_cbranch_execz .LBB0_2
	v_mov_b32_e32 v2, 0
	v_mov_b32_e32 v3, v2
	v_mov_b32_e32 v4, v2
	v_mov_b32_e32 v5, v2
	v_mov_b32_e32 v1, 0x20000
	ds_write_b128 v1, v[2:5]

.LBB0_219:
	v_lshrrev_b32_e32 v1, 3, v162
	v_lshrrev_b32_e32 v156, 2, v162
	v_and_b32_e32 v154, 0x70, v1
	v_and_b32_e32 v155, 15, v162
	s_andn2_b64 vcc, exec, s[2:3]
	v_bfe_u32 v157, v162, 4, 2
	s_cbranch_vccnz .LBB0_576
	s_cmp_lg_u32 s99, 0
	s_cbranch_scc1 .Lp1m_go
	s_cmpk_lt_u32 s92, 0x80
	s_cbranch_scc1 .Lp1m_go
	s_mov_b32 s99, 1
	s_branch .Lp1m_mini
.Lp1m_go:
	v_lshlrev_b32_e32 v3, 4, v162
	v_and_b32_e32 v2, 32, v162
	v_and_b32_e32 v16, 15, v156
	v_bitop3_b32 v14, v3, v2, 48 bitop3:0x6c
	v_and_b32_e32 v15, 64, v162
	v_or_b32_e32 v2, v14, v15
	s_lshl_b32 s1, s0, 1
	v_or_b32_e32 v4, v154, v16
	v_mad_u64_u32 v[130:131], s[4:5], s1, v4, v[2:3]
	v_add_u32_e32 v3, 0x2000, v3
	v_lshrrev_b32_e32 v3, 7, v3
	v_and_b32_e32 v17, 0xf0, v3
	v_or_b32_e32 v3, v17, v16
	v_mad_u64_u32 v[132:133], s[4:5], s1, v3, v[2:3]
	s_ashr_i32 s1, s0, 31
	s_lshl_b64 s[20:21], s[0:1], 9
	s_ashr_i32 s4, s13, 31
	s_mul_i32 s4, s20, s4
	s_mul_hi_u32 s5, s20, s13
	s_ashr_i32 s7, s12, 31
	s_add_i32 s6, s5, s4
	s_lshr_b64 s[4:5], s[0:1], 23
	s_mul_i32 s7, s20, s7
	s_mul_hi_u32 s8, s20, s12
	s_lshr_b32 s3, s28, 6
	s_mul_i32 s5, s4, s13
	s_add_i32 s7, s8, s7
	s_mul_i32 s4, s4, s12
	s_lshr_b32 s2, s28, 8
	s_lshl_b64 s[18:19], s[0:1], 8
	s_lshl_b32 s29, s3, 10
	s_add_i32 s6, s6, s5
	s_add_i32 s7, s7, s4
	s_mul_i32 s4, s20, s12
	s_add_u32 s8, s86, s4
	s_mul_i32 s5, s20, s13
	s_addc_u32 s9, s87, s7
	s_add_i32 s30, s29, 0x10000
	s_add_i32 s31, s29, 0x12000
	s_mov_b32 m0, s30
	s_add_u32 s10, s58, s5
	global_load_lds_dwordx4 v130, s[8:9]
	s_mov_b32 m0, s31
	s_addc_u32 s11, s59, s6
	s_add_i32 s33, s29, 0x2000
	global_load_lds_dwordx4 v132, s[8:9]
	s_mov_b32 m0, s29
	s_add_u32 s4, s8, s18
	global_load_lds_dwordx4 v130, s[10:11]
	s_mov_b32 m0, s33
	s_addc_u32 s5, s9, s19
	s_add_i32 s34, s29, 0x14000
	s_add_i32 s35, s29, 0x16000
	global_load_lds_dwordx4 v132, s[10:11]
	s_mov_b32 m0, s34
	s_add_u32 s6, s10, s18
	global_load_lds_dwordx4 v130, s[4:5]
	s_mov_b32 m0, s35
	s_addc_u32 s7, s11, s19
	s_add_i32 s38, s29, 0x4000
	global_load_lds_dwordx4 v132, s[4:5]
	s_mov_b32 m0, s38
	s_add_i32 s39, s29, 0x6000
	global_load_lds_dwordx4 v130, s[6:7]
	s_mov_b32 m0, s39
	v_mov_b32_e32 v135, 0
	global_load_lds_dwordx4 v132, s[6:7]
	v_mov_b32_e32 v131, v135
	v_mov_b32_e32 v133, v135
	v_lshl_add_u64 v[12:13], s[8:9], 0, v[130:131]
	v_lshl_add_u64 v[10:11], s[8:9], 0, v[132:133]
	v_lshl_add_u64 v[8:9], s[10:11], 0, v[130:131]
	v_lshl_add_u64 v[6:7], s[10:11], 0, v[132:133]
	v_lshl_add_u64 v[4:5], s[4:5], 0, v[130:131]
	v_lshl_add_u64 v[2:3], s[4:5], 0, v[132:133]
	s_cmp_lg_u32 s2, 1
	s_movk_i32 s40, 0x4000
	s_cbranch_scc1 .LBB0_222
	s_barrier

.LBB0_576:
	s_cmp_eq_u32 s99, 2
	s_cbranch_scc1 .LBB0_599

.LBB0_599:
	s_cmp_lg_u32 s99, 1
	s_cbranch_scc1 .Lp1m_cont
	s_mov_b32 s99, 2
	s_waitcnt lgkmcnt(0)
	s_barrier
	s_branch .LBB0_213
